# A/C loop: window-mask scalar test moved behind the last QK MFMA so it supplies MFMA-to-VALU wait states (s_nop 8 becomes s_nop 2)
# baseline (speedup 1.0000x reference)
; #define MFMA(a, b, c) __builtin_amdgcn_mfma_f32_32x32x16_bf16((a), (b), (c), 0, 0, 0)
; template <int DV> ...
;     const float THR = 8.f;
;     f32x16 S[2];
; #pragma unroll
;     for (int sub = 0; sub < 2; sub++) {
;         const bf16x8 kf = *(const bf16x8*)(Kl + (sub * 32 + l31) * LROW + hh * 16);
;         S[sub] = MFMA(kf, qf[0], NEGM);
;     }
; #pragma unroll
;     for (int kk = 1; kk < 4; kk++)
; #pragma unroll
;         for (int sub = 0; sub < 2; sub++) {
;             const bf16x8 kf = *(const bf16x8*)(Kl + (sub * 32 + l31) * LROW + kk * 32 + hh * 16);
;             S[sub] = MFMA(kf, qf[kk], S[sub]);
;         }
;     if (domask) {
; #pragma unroll
;         for (int sub = 0; sub < 2; sub++)
; #pragma unroll
;             for (int r = 0; r < 16; r++) {
;                 const int d = qpos - (kpos0 + sub * 32 + (r & 3) + 8 * (r >> 2) + 4 * hh);
;                 S[sub][r] = (d <= 128 && d >= -128) ? S[sub][r] : -1e30f;
;             }
.LBB0_484:
	s_bitcmp1_b32 s16, 0
	s_cselect_b32 s16, 0x4800, 0
	v_add_u32_e32 v120, s16, v117
	ds_read_b128 v[192:195], v120
	ds_read_b128 v[196:199], v120 offset:4608
	ds_read_b128 v[200:203], v120 offset:32
	ds_read_b128 v[204:207], v120 offset:4640
	ds_read_b128 v[208:211], v120 offset:64
	ds_read_b128 v[212:215], v120 offset:4672
	ds_read_b128 v[216:219], v120 offset:96
	ds_read_b128 v[220:223], v120 offset:4704
	ds_read_b128 v[224:227], v120 offset:9216
	ds_read_b128 v[228:231], v120 offset:13824
	ds_read_b128 v[232:235], v120 offset:13856
	ds_read_b128 v[236:239], v120 offset:9248
	ds_read_b128 v[240:243], v120 offset:9280
	ds_read_b128 v[244:247], v120 offset:13888
	ds_read_b128 v[134:137], v120 offset:9312
	s_waitcnt lgkmcnt(13)
	v_mfma_f32_32x32x16_bf16 v[66:81], v[192:195], v[82:85], v[34:49]
	v_mfma_f32_32x32x16_bf16 v[50:65], v[196:199], v[82:85], v[34:49]
	ds_read_b128 v[138:141], v120 offset:13920
	s_waitcnt lgkmcnt(12)
	v_mfma_f32_32x32x16_bf16 v[66:81], v[200:203], v[86:89], v[66:81]
	v_mfma_f32_32x32x16_bf16 v[50:65], v[204:207], v[86:89], v[50:65]
	s_waitcnt lgkmcnt(10)
	v_mfma_f32_32x32x16_bf16 v[66:81], v[208:211], v[90:93], v[66:81]
	v_mfma_f32_32x32x16_bf16 v[50:65], v[212:215], v[90:93], v[50:65]
	s_waitcnt lgkmcnt(9)
	v_mfma_f32_32x32x16_bf16 v[66:81], v[216:219], v[94:97], v[66:81]
	s_waitcnt lgkmcnt(8)
	v_mfma_f32_32x32x16_bf16 v[50:65], v[220:223], v[94:97], v[50:65]
	s_add_i32 s16, s77, s30
	s_addk_i32 s16, 0xfebe
	s_cmp_lt_u32 s16, 0xffffff5d
	s_cselect_b64 s[16:17], -1, 0
	s_and_b64 s[16:17], s[0:1], s[16:17]
	s_andn2_b64 vcc, exec, s[16:17]
	s_cbranch_vccnz .LBB0_486
	v_add_u32_e32 v121, 59, v119
	s_movk_i32 s17, 0x101
	v_cmp_gt_u32_e32 vcc, s17, v121
	v_add_u32_e32 v121, s30, v118
	s_movk_i32 s16, 0xfefe
	s_nop 3
	v_cndmask_b32_e32 v66, v187, v66, vcc
	v_cmp_lt_u32_e32 vcc, s16, v121
	v_add_u32_e32 v121, 57, v119
	s_nop 0
	v_cndmask_b32_e32 v67, v187, v67, vcc
	v_cmp_gt_u32_e32 vcc, s17, v121
	v_add_u32_e32 v121, 56, v119
	s_nop 0
	v_cndmask_b32_e32 v68, v187, v68, vcc
	v_cmp_gt_u32_e32 vcc, s17, v121
	v_add_u32_e32 v121, 51, v119
	s_nop 0
	v_cndmask_b32_e32 v69, v187, v69, vcc
	v_cmp_gt_u32_e32 vcc, s17, v121
	v_add_u32_e32 v121, 50, v119
	s_nop 0
	v_cndmask_b32_e32 v70, v187, v70, vcc
	v_cmp_gt_u32_e32 vcc, s17, v121
	v_add_u32_e32 v121, 49, v119
	s_nop 0
	v_cndmask_b32_e32 v71, v187, v71, vcc
	v_cmp_gt_u32_e32 vcc, s17, v121
	v_add_u32_e32 v121, 48, v119
	s_nop 0
	v_cndmask_b32_e32 v72, v187, v72, vcc
	v_cmp_gt_u32_e32 vcc, s17, v121
	v_add_u32_e32 v121, 43, v119
	s_nop 0
	v_cndmask_b32_e32 v73, v187, v73, vcc
	v_cmp_gt_u32_e32 vcc, s17, v121
	v_add_u32_e32 v121, 42, v119
	s_nop 0
	v_cndmask_b32_e32 v74, v187, v74, vcc
	v_cmp_gt_u32_e32 vcc, s17, v121
	v_add_u32_e32 v121, 41, v119
	s_nop 0
	v_cndmask_b32_e32 v75, v187, v75, vcc
	v_cmp_gt_u32_e32 vcc, s17, v121
	v_add_u32_e32 v121, 40, v119
	s_nop 0
	v_cndmask_b32_e32 v76, v187, v76, vcc
	v_cmp_gt_u32_e32 vcc, s17, v121
	v_add_u32_e32 v121, 35, v119
	s_nop 0
	v_cndmask_b32_e32 v77, v187, v77, vcc
	v_cmp_gt_u32_e32 vcc, s17, v121
	v_add_u32_e32 v121, 34, v119
	s_nop 0
	v_cndmask_b32_e32 v78, v187, v78, vcc
	v_cmp_gt_u32_e32 vcc, s17, v121
	v_add_u32_e32 v121, 33, v119
	s_nop 0
	v_cndmask_b32_e32 v79, v187, v79, vcc
	v_cmp_gt_u32_e32 vcc, s17, v121
	v_add_u32_e32 v121, 32, v119
	s_nop 0
	v_cndmask_b32_e32 v80, v187, v80, vcc
	v_cmp_gt_u32_e32 vcc, s17, v121
	v_add_u32_e32 v121, 27, v119
	s_nop 0
	v_cndmask_b32_e32 v81, v187, v81, vcc
	v_cmp_gt_u32_e32 vcc, s17, v121
	v_add_u32_e32 v121, 26, v119
	s_nop 0
	v_cndmask_b32_e32 v50, v187, v50, vcc
	v_cmp_gt_u32_e32 vcc, s17, v121
	v_add_u32_e32 v121, 25, v119
	s_nop 0
	v_cndmask_b32_e32 v51, v187, v51, vcc
	v_cmp_gt_u32_e32 vcc, s17, v121
	v_add_u32_e32 v121, 24, v119
	s_nop 0
	v_cndmask_b32_e32 v52, v187, v52, vcc
	v_cmp_gt_u32_e32 vcc, s17, v121
	v_add_u32_e32 v121, 19, v119
	s_nop 0
	v_cndmask_b32_e32 v53, v187, v53, vcc
	v_cmp_gt_u32_e32 vcc, s17, v121
	v_add_u32_e32 v121, 18, v119
	s_nop 0
	v_cndmask_b32_e32 v54, v187, v54, vcc
	v_cmp_gt_u32_e32 vcc, s17, v121
	v_add_u32_e32 v121, 17, v119
	s_nop 0
	v_cndmask_b32_e32 v55, v187, v55, vcc
	v_cmp_gt_u32_e32 vcc, s17, v121
	v_add_u32_e32 v121, 16, v119
	s_nop 0
	v_cndmask_b32_e32 v56, v187, v56, vcc
	v_cmp_gt_u32_e32 vcc, s17, v121
	v_add_u32_e32 v121, 11, v119
	s_nop 0
	v_cndmask_b32_e32 v57, v187, v57, vcc
	v_cmp_gt_u32_e32 vcc, s17, v121
	v_add_u32_e32 v121, 10, v119
	s_nop 0
	v_cndmask_b32_e32 v58, v187, v58, vcc
	v_cmp_gt_u32_e32 vcc, s17, v121
	v_add_u32_e32 v121, 9, v119
	s_nop 0
	v_cndmask_b32_e32 v59, v187, v59, vcc
	v_cmp_gt_u32_e32 vcc, s17, v121
	v_add_u32_e32 v121, 8, v119
	s_nop 0
	v_cndmask_b32_e32 v60, v187, v60, vcc
	v_cmp_gt_u32_e32 vcc, s17, v121
	v_add_u32_e32 v121, 3, v119
	s_nop 0
	v_cndmask_b32_e32 v61, v187, v61, vcc
	v_cmp_gt_u32_e32 vcc, s17, v121
	v_add_u32_e32 v121, 2, v119
	s_nop 0
	v_cndmask_b32_e32 v62, v187, v62, vcc
	v_cmp_gt_u32_e32 vcc, s17, v121
	v_add_u32_e32 v121, 1, v119
	s_nop 0
	v_cndmask_b32_e32 v63, v187, v63, vcc
	v_cmp_gt_u32_e32 vcc, s17, v121
	s_nop 1
	v_cndmask_b32_e32 v64, v187, v64, vcc
	v_cmp_gt_u32_e32 vcc, s17, v119
	s_nop 1
	v_cndmask_b32_e32 v65, v187, v65, vcc
; template <int DV> ...
;     ...
;     float mx = S[0][0];
; #pragma unroll
;     for (int sub = 0; sub < 2; sub++)
; #pragma unroll
;         for (int r = 0; r < 16; r++) mx = fmaxf(mx, S[sub][r]);
;     mx = fmaxf(mx, __shfl_xor(mx, 32));
;     if (first || __any(mx > THR)) {
;         const float d = first ? mx : fmaxf(mx, 0.f);
;         const float alpha = __builtin_amdgcn_exp2f(-d);
;         m += d; l *= alpha;
; #pragma unroll
;         for (int dt = 0; dt < DV / 32; dt++)
; #pragma unroll
;             for (int r = 0; r < 16; r++) O[dt][r] *= alpha;
; #pragma unroll
;         for (int r = 0; r < 16; r++) NEGM[r] -= d;
; #pragma unroll
;         for (int sub = 0; sub < 2; sub++)
; #pragma unroll
;             for (int r = 0; r < 16; r++) S[sub][r] -= d;
.LBB0_486:
	s_nop 2
	v_max3_f32 v121, v66, v67, v68
	v_max3_f32 v121, v121, v69, v70
	v_max3_f32 v121, v121, v71, v72
	v_max3_f32 v121, v121, v73, v74
	v_max3_f32 v122, v50, v51, v52
	v_max3_f32 v121, v121, v75, v76
	v_max3_f32 v122, v122, v53, v54
	v_max3_f32 v121, v121, v77, v78
	v_max3_f32 v122, v122, v55, v56
	v_max3_f32 v121, v121, v79, v80
	v_max3_f32 v122, v122, v57, v58
	v_max3_f32 v122, v122, v59, v60
	v_max3_f32 v122, v122, v61, v62
	v_max3_f32 v122, v122, v63, v64
	v_max3_f32 v121, v121, v81, v65
	v_max_f32_e32 v121, v121, v122
	v_mov_b32_e32 v122, v121
	s_nop 1
	v_permlane32_swap_b32_e32 v121, v122
	v_max_f32_e32 v121, v121, v122
	v_cmp_lt_f32_e32 vcc, s39, v121
	s_cbranch_vccz .LBB0_488
	v_max_f32_e32 v121, v121, v121
	v_max_f32_e32 v122, 0, v121
	v_exp_f32_e64 v124, -v122
	v_add_f32_e32 v111, v111, v122
	v_sub_f32_e32 v49, v49, v122
	v_sub_f32_e32 v48, v48, v122
	v_mul_f32_e32 v110, v110, v124
	v_pk_mul_f32 v[16:17], v[16:17], v[124:125] op_sel_hi:[1,0]
	v_pk_mul_f32 v[14:15], v[14:15], v[124:125] op_sel_hi:[1,0]
	v_pk_mul_f32 v[12:13], v[12:13], v[124:125] op_sel_hi:[1,0]
	v_pk_mul_f32 v[10:11], v[10:11], v[124:125] op_sel_hi:[1,0]
	v_pk_mul_f32 v[8:9], v[8:9], v[124:125] op_sel_hi:[1,0]
	v_pk_mul_f32 v[6:7], v[6:7], v[124:125] op_sel_hi:[1,0]
	v_pk_mul_f32 v[4:5], v[4:5], v[124:125] op_sel_hi:[1,0]
	v_pk_mul_f32 v[2:3], v[2:3], v[124:125] op_sel_hi:[1,0]
	v_pk_mul_f32 v[32:33], v[32:33], v[124:125] op_sel_hi:[1,0]
	v_pk_mul_f32 v[30:31], v[30:31], v[124:125] op_sel_hi:[1,0]
	v_pk_mul_f32 v[28:29], v[28:29], v[124:125] op_sel_hi:[1,0]
	v_pk_mul_f32 v[26:27], v[26:27], v[124:125] op_sel_hi:[1,0]
	v_pk_mul_f32 v[24:25], v[24:25], v[124:125] op_sel_hi:[1,0]
	v_pk_mul_f32 v[22:23], v[22:23], v[124:125] op_sel_hi:[1,0]
	v_pk_mul_f32 v[20:21], v[20:21], v[124:125] op_sel_hi:[1,0]
	v_pk_mul_f32 v[18:19], v[18:19], v[124:125] op_sel_hi:[1,0]
	v_sub_f32_e32 v47, v47, v122
	v_sub_f32_e32 v46, v46, v122
	v_sub_f32_e32 v45, v45, v122
	v_sub_f32_e32 v44, v44, v122
	v_sub_f32_e32 v43, v43, v122
	v_sub_f32_e32 v42, v42, v122
	v_sub_f32_e32 v41, v41, v122
	v_sub_f32_e32 v40, v40, v122
	v_sub_f32_e32 v39, v39, v122
	v_sub_f32_e32 v38, v38, v122
	v_sub_f32_e32 v37, v37, v122
	v_sub_f32_e32 v36, v36, v122
	v_sub_f32_e32 v35, v35, v122
	v_sub_f32_e32 v34, v34, v122
	v_pk_add_f32 v[66:67], v[66:67], v[122:123] op_sel_hi:[1,0] neg_lo:[0,1] neg_hi:[0,1]
	v_pk_add_f32 v[68:69], v[68:69], v[122:123] op_sel_hi:[1,0] neg_lo:[0,1] neg_hi:[0,1]
	v_pk_add_f32 v[70:71], v[70:71], v[122:123] op_sel_hi:[1,0] neg_lo:[0,1] neg_hi:[0,1]
	v_pk_add_f32 v[72:73], v[72:73], v[122:123] op_sel_hi:[1,0] neg_lo:[0,1] neg_hi:[0,1]
	v_pk_add_f32 v[74:75], v[74:75], v[122:123] op_sel_hi:[1,0] neg_lo:[0,1] neg_hi:[0,1]
	v_pk_add_f32 v[76:77], v[76:77], v[122:123] op_sel_hi:[1,0] neg_lo:[0,1] neg_hi:[0,1]
	v_pk_add_f32 v[78:79], v[78:79], v[122:123] op_sel_hi:[1,0] neg_lo:[0,1] neg_hi:[0,1]
	v_pk_add_f32 v[80:81], v[80:81], v[122:123] op_sel_hi:[1,0] neg_lo:[0,1] neg_hi:[0,1]
	v_pk_add_f32 v[50:51], v[50:51], v[122:123] op_sel_hi:[1,0] neg_lo:[0,1] neg_hi:[0,1]
	v_pk_add_f32 v[52:53], v[52:53], v[122:123] op_sel_hi:[1,0] neg_lo:[0,1] neg_hi:[0,1]
	v_pk_add_f32 v[54:55], v[54:55], v[122:123] op_sel_hi:[1,0] neg_lo:[0,1] neg_hi:[0,1]
	v_pk_add_f32 v[56:57], v[56:57], v[122:123] op_sel_hi:[1,0] neg_lo:[0,1] neg_hi:[0,1]
	v_pk_add_f32 v[58:59], v[58:59], v[122:123] op_sel_hi:[1,0] neg_lo:[0,1] neg_hi:[0,1]
	v_pk_add_f32 v[60:61], v[60:61], v[122:123] op_sel_hi:[1,0] neg_lo:[0,1] neg_hi:[0,1]
	v_pk_add_f32 v[62:63], v[62:63], v[122:123] op_sel_hi:[1,0] neg_lo:[0,1] neg_hi:[0,1]
	v_pk_add_f32 v[64:65], v[64:65], v[122:123] op_sel_hi:[1,0] neg_lo:[0,1] neg_hi:[0,1]
